# att: second query tile's QK fragment reads prefetched two key tiles ahead into three rotating register sets, counted lgkmcnt waits
# baseline (speedup 1.0000x reference)
.LBB0_280:
	s_or_b64 exec, exec, s[14:15]
	ds_read_b128 v[176:179], v236
	ds_read_b128 v[180:183], v236 offset:64
	ds_read_b128 v[184:187], v236 offset:2304
	ds_read_b128 v[188:191], v236 offset:2368
	ds_read_b128 v[192:195], v236 offset:4608
	ds_read_b128 v[196:199], v236 offset:4672
	v_readlane_b32 s38, v255, 18
	s_add_i32 s35, s35, s25
	s_and_b64 vcc, exec, s[58:59]
	s_waitcnt lgkmcnt(5)
	v_mfma_f32_16x16x32_bf16 v[64:67], v[176:179], v[4:7], 0
	v_readlane_b32 s39, v255, 19
	s_waitcnt lgkmcnt(4)
	v_mfma_f32_16x16x32_bf16 v[64:67], v[180:183], v[0:3], v[64:67]
	s_nop 7
	v_fma_f32 v64, v64, s18, -v69
	v_fma_f32 v65, v65, s18, -v71
	v_pk_fma_f32 v[66:67], v[66:67], s[18:19], v[72:73] op_sel_hi:[1,0,1] neg_lo:[0,0,1] neg_hi:[0,0,1]
	v_cndmask_b32_e64 v110, v218, v64, s[42:43]
	v_cndmask_b32_e64 v106, v218, v65, s[44:45]
	v_cndmask_b32_e64 v64, v218, v67, s[46:47]
	v_cndmask_b32_e64 v65, v218, v66, s[48:49]
	s_cbranch_vccnz .LBB0_282
	v_or_b32_e32 v66, s35, v112
	s_cmp_gt_i32 s35, -1
	s_cselect_b64 s[14:15], -1, 0
	v_cmp_gt_i32_e32 vcc, s29, v66
	s_and_b64 vcc, s[14:15], vcc
	v_or_b32_e32 v67, 1, v66
	v_cndmask_b32_e32 v110, v218, v110, vcc
	v_cmp_gt_i32_e32 vcc, s29, v67
	s_and_b64 vcc, s[14:15], vcc
	v_or_b32_e32 v67, 2, v66
	v_cndmask_b32_e32 v106, v218, v106, vcc
	v_cmp_gt_i32_e32 vcc, s29, v67
	s_and_b64 vcc, s[14:15], vcc
	v_or_b32_e32 v66, 3, v66
	v_cndmask_b32_e32 v65, v218, v65, vcc
	v_cmp_gt_i32_e32 vcc, s29, v66
	s_and_b64 vcc, s[14:15], vcc
	s_nop 0
	v_cndmask_b32_e32 v64, v218, v64, vcc
.LBB0_282:
	ds_read_b128 v[176:179], v236 offset:6912
	ds_read_b128 v[180:183], v236 offset:6976
	s_and_b64 vcc, exec, s[58:59]
	s_waitcnt lgkmcnt(5)
	v_mfma_f32_16x16x32_bf16 v[66:69], v[184:187], v[4:7], 0
	s_waitcnt lgkmcnt(4)
	v_mfma_f32_16x16x32_bf16 v[66:69], v[188:191], v[0:3], v[66:69]
	s_nop 7
	v_pk_fma_f32 v[108:109], v[66:67], s[18:19], v[74:75] op_sel_hi:[1,0,1] neg_lo:[0,0,1] neg_hi:[0,0,1]
	v_pk_fma_f32 v[66:67], v[68:69], s[18:19], v[76:77] op_sel_hi:[1,0,1] neg_lo:[0,0,1] neg_hi:[0,0,1]
	s_cbranch_vccnz .LBB0_284
	v_add_u32_e32 v68, s35, v234
	s_cmpk_gt_i32 s35, 0xffef
	s_cselect_b64 s[14:15], -1, 0
	v_cmp_gt_i32_e32 vcc, s29, v68
	s_and_b64 vcc, s[14:15], vcc
	v_or_b32_e32 v69, 1, v68
	v_cndmask_b32_e32 v108, v218, v108, vcc
	v_cmp_gt_i32_e32 vcc, s29, v69
	s_and_b64 vcc, s[14:15], vcc
	v_or_b32_e32 v69, 2, v68
	v_cndmask_b32_e32 v109, v218, v109, vcc
	v_cmp_gt_i32_e32 vcc, s29, v69
	s_and_b64 vcc, s[14:15], vcc
	v_or_b32_e32 v68, 3, v68
	v_cndmask_b32_e32 v66, v218, v66, vcc
	v_cmp_gt_i32_e32 vcc, s29, v68
	s_and_b64 vcc, s[14:15], vcc
	s_nop 0
	v_cndmask_b32_e32 v67, v218, v67, vcc
.LBB0_284:
	ds_read_b128 v[184:187], v236 offset:9216
	ds_read_b128 v[188:191], v236 offset:9280
	s_and_b64 vcc, exec, s[58:59]
	s_waitcnt lgkmcnt(5)
	v_mfma_f32_16x16x32_bf16 v[68:71], v[192:195], v[4:7], 0
	s_waitcnt lgkmcnt(4)
	v_mfma_f32_16x16x32_bf16 v[70:73], v[196:199], v[0:3], v[68:71]
	s_nop 7
	v_pk_fma_f32 v[70:71], v[70:71], s[18:19], v[78:79] op_sel_hi:[1,0,1] neg_lo:[0,0,1] neg_hi:[0,0,1]
	v_pk_fma_f32 v[68:69], v[72:73], s[18:19], v[80:81] op_sel_hi:[1,0,1] neg_lo:[0,0,1] neg_hi:[0,0,1]
	s_cbranch_vccnz .LBB0_286
	v_add_u32_e32 v72, s35, v228
	s_cmpk_gt_i32 s35, 0xffdf
	s_cselect_b64 s[14:15], -1, 0
	v_cmp_gt_i32_e32 vcc, s29, v72
	s_and_b64 vcc, s[14:15], vcc
	v_or_b32_e32 v73, 1, v72
	v_cndmask_b32_e32 v70, v218, v70, vcc
	v_cmp_gt_i32_e32 vcc, s29, v73
	s_and_b64 vcc, s[14:15], vcc
	v_or_b32_e32 v73, 2, v72
	v_cndmask_b32_e32 v71, v218, v71, vcc
	v_cmp_gt_i32_e32 vcc, s29, v73
	s_and_b64 vcc, s[14:15], vcc
	v_or_b32_e32 v72, 3, v72
	v_cndmask_b32_e32 v68, v218, v68, vcc
	v_cmp_gt_i32_e32 vcc, s29, v72
	s_and_b64 vcc, s[14:15], vcc
	s_nop 0
	v_cndmask_b32_e32 v69, v218, v69, vcc
.LBB0_286:
	ds_read_b128 v[192:195], v236 offset:11520
	ds_read_b128 v[196:199], v236 offset:11584
	s_and_b64 vcc, exec, s[58:59]
	s_waitcnt lgkmcnt(5)
	v_mfma_f32_16x16x32_bf16 v[72:75], v[176:179], v[4:7], 0
	s_waitcnt lgkmcnt(4)
	v_mfma_f32_16x16x32_bf16 v[74:77], v[180:183], v[0:3], v[72:75]
	s_nop 7
	v_pk_fma_f32 v[74:75], v[74:75], s[18:19], v[82:83] op_sel_hi:[1,0,1] neg_lo:[0,0,1] neg_hi:[0,0,1]
	v_pk_fma_f32 v[72:73], v[76:77], s[18:19], v[84:85] op_sel_hi:[1,0,1] neg_lo:[0,0,1] neg_hi:[0,0,1]
	s_cbranch_vccnz .LBB0_288
	v_add_u32_e32 v76, s35, v229
	s_cmpk_gt_i32 s35, 0xffcf
	s_cselect_b64 s[14:15], -1, 0
	v_cmp_gt_i32_e32 vcc, s29, v76
	s_and_b64 vcc, s[14:15], vcc
	v_or_b32_e32 v77, 1, v76
	v_cndmask_b32_e32 v74, v218, v74, vcc
	v_cmp_gt_i32_e32 vcc, s29, v77
	s_and_b64 vcc, s[14:15], vcc
	v_or_b32_e32 v77, 2, v76
	v_cndmask_b32_e32 v75, v218, v75, vcc
	v_cmp_gt_i32_e32 vcc, s29, v77
	s_and_b64 vcc, s[14:15], vcc
	v_or_b32_e32 v76, 3, v76
	v_cndmask_b32_e32 v72, v218, v72, vcc
	v_cmp_gt_i32_e32 vcc, s29, v76
	s_and_b64 vcc, s[14:15], vcc
	s_nop 0
	v_cndmask_b32_e32 v73, v218, v73, vcc
.LBB0_288:
	ds_read_b128 v[176:179], v236 offset:13824
	ds_read_b128 v[180:183], v236 offset:13888
	s_and_b64 vcc, exec, s[58:59]
	s_waitcnt lgkmcnt(5)
	v_mfma_f32_16x16x32_bf16 v[76:79], v[184:187], v[4:7], 0
	s_waitcnt lgkmcnt(4)
	v_mfma_f32_16x16x32_bf16 v[76:79], v[188:191], v[0:3], v[76:79]
	s_nop 7
	v_pk_fma_f32 v[82:83], v[76:77], s[18:19], v[86:87] op_sel_hi:[1,0,1] neg_lo:[0,0,1] neg_hi:[0,0,1]
	v_pk_fma_f32 v[80:81], v[78:79], s[18:19], v[88:89] op_sel_hi:[1,0,1] neg_lo:[0,0,1] neg_hi:[0,0,1]
	s_cbranch_vccnz .LBB0_290
	s_add_i32 s34, s34, s25
	v_or_b32_e32 v76, s34, v112
	s_cmp_gt_i32 s34, -1
	s_cselect_b64 s[14:15], -1, 0
	v_cmp_gt_i32_e32 vcc, s29, v76
	s_and_b64 vcc, s[14:15], vcc
	v_or_b32_e32 v77, 1, v76
	v_cndmask_b32_e32 v82, v218, v82, vcc
	v_cmp_gt_i32_e32 vcc, s29, v77
	s_and_b64 vcc, s[14:15], vcc
	v_or_b32_e32 v77, 2, v76
	v_cndmask_b32_e32 v83, v218, v83, vcc
	v_cmp_gt_i32_e32 vcc, s29, v77
	s_and_b64 vcc, s[14:15], vcc
	v_or_b32_e32 v76, 3, v76
	v_cndmask_b32_e32 v80, v218, v80, vcc
	v_cmp_gt_i32_e32 vcc, s29, v76
	s_and_b64 vcc, s[14:15], vcc
	s_nop 0
	v_cndmask_b32_e32 v81, v218, v81, vcc
.LBB0_290:
	ds_read_b128 v[184:187], v236 offset:16128
	ds_read_b128 v[188:191], v236 offset:16192
	s_and_b64 vcc, exec, s[58:59]
	s_waitcnt lgkmcnt(5)
	v_mfma_f32_16x16x32_bf16 v[76:79], v[192:195], v[4:7], 0
	s_waitcnt lgkmcnt(4)
	v_mfma_f32_16x16x32_bf16 v[76:79], v[196:199], v[0:3], v[76:79]
	s_nop 7
	v_pk_fma_f32 v[86:87], v[76:77], s[18:19], v[90:91] op_sel_hi:[1,0,1] neg_lo:[0,0,1] neg_hi:[0,0,1]
	v_pk_fma_f32 v[84:85], v[78:79], s[18:19], v[92:93] op_sel_hi:[1,0,1] neg_lo:[0,0,1] neg_hi:[0,0,1]
	s_cbranch_vccnz .LBB0_292
	v_add_u32_e32 v76, s35, v230
	s_cmpk_gt_i32 s35, 0xffaf
	s_cselect_b64 s[14:15], -1, 0
	v_cmp_gt_i32_e32 vcc, s29, v76
	s_and_b64 vcc, s[14:15], vcc
	v_or_b32_e32 v77, 1, v76
	v_cndmask_b32_e32 v86, v218, v86, vcc
	v_cmp_gt_i32_e32 vcc, s29, v77
	s_and_b64 vcc, s[14:15], vcc
	v_or_b32_e32 v77, 2, v76
	v_cndmask_b32_e32 v87, v218, v87, vcc
	v_cmp_gt_i32_e32 vcc, s29, v77
	s_and_b64 vcc, s[14:15], vcc
	v_or_b32_e32 v76, 3, v76
	v_cndmask_b32_e32 v84, v218, v84, vcc
	v_cmp_gt_i32_e32 vcc, s29, v76
	s_and_b64 vcc, s[14:15], vcc
	s_nop 0
	v_cndmask_b32_e32 v85, v218, v85, vcc
.LBB0_292:
	ds_read_b128 v[192:195], v236 offset:18432
	ds_read_b128 v[196:199], v236 offset:18496
	s_and_b64 vcc, exec, s[58:59]
	s_waitcnt lgkmcnt(5)
	v_mfma_f32_16x16x32_bf16 v[76:79], v[176:179], v[4:7], 0
	s_waitcnt lgkmcnt(4)
	v_mfma_f32_16x16x32_bf16 v[76:79], v[180:183], v[0:3], v[76:79]
	s_nop 7
	v_pk_fma_f32 v[90:91], v[76:77], s[18:19], v[94:95] op_sel_hi:[1,0,1] neg_lo:[0,0,1] neg_hi:[0,0,1]
	v_pk_fma_f32 v[88:89], v[78:79], s[18:19], v[96:97] op_sel_hi:[1,0,1] neg_lo:[0,0,1] neg_hi:[0,0,1]
	s_cbranch_vccnz .LBB0_294
	v_add_u32_e32 v76, s35, v231
	s_cmpk_gt_i32 s35, 0xff9f
	s_cselect_b64 s[14:15], -1, 0
	v_cmp_gt_i32_e32 vcc, s29, v76
	s_and_b64 vcc, s[14:15], vcc
	v_or_b32_e32 v77, 1, v76
	v_cndmask_b32_e32 v90, v218, v90, vcc
	v_cmp_gt_i32_e32 vcc, s29, v77
	s_and_b64 vcc, s[14:15], vcc
	v_or_b32_e32 v77, 2, v76
	v_cndmask_b32_e32 v91, v218, v91, vcc
	v_cmp_gt_i32_e32 vcc, s29, v77
	s_and_b64 vcc, s[14:15], vcc
	v_or_b32_e32 v76, 3, v76
	v_cndmask_b32_e32 v88, v218, v88, vcc
	v_cmp_gt_i32_e32 vcc, s29, v76
	s_and_b64 vcc, s[14:15], vcc
	s_nop 0
	v_cndmask_b32_e32 v89, v218, v89, vcc
.LBB0_294:
	s_and_b64 vcc, exec, s[58:59]
	s_waitcnt lgkmcnt(3)
	v_mfma_f32_16x16x32_bf16 v[76:79], v[184:187], v[4:7], 0
	s_waitcnt lgkmcnt(2)
	v_mfma_f32_16x16x32_bf16 v[76:79], v[188:191], v[0:3], v[76:79]
	s_nop 7
	v_pk_fma_f32 v[94:95], v[76:77], s[18:19], v[98:99] op_sel_hi:[1,0,1] neg_lo:[0,0,1] neg_hi:[0,0,1]
	v_pk_fma_f32 v[92:93], v[78:79], s[18:19], v[100:101] op_sel_hi:[1,0,1] neg_lo:[0,0,1] neg_hi:[0,0,1]
	s_cbranch_vccnz .LBB0_296
	v_add_u32_e32 v76, s35, v232
	s_cmpk_gt_i32 s35, 0xff8f
	s_cselect_b64 s[14:15], -1, 0
	v_cmp_gt_i32_e32 vcc, s29, v76
	s_and_b64 vcc, s[14:15], vcc
	v_or_b32_e32 v77, 1, v76
	v_cndmask_b32_e32 v94, v218, v94, vcc
	v_cmp_gt_i32_e32 vcc, s29, v77
	s_and_b64 vcc, s[14:15], vcc
	v_or_b32_e32 v77, 2, v76
	v_cndmask_b32_e32 v95, v218, v95, vcc
	v_cmp_gt_i32_e32 vcc, s29, v77
	s_and_b64 vcc, s[14:15], vcc
	v_or_b32_e32 v76, 3, v76
	v_cndmask_b32_e32 v92, v218, v92, vcc
	v_cmp_gt_i32_e32 vcc, s29, v76
	s_and_b64 vcc, s[14:15], vcc
	s_nop 0
	v_cndmask_b32_e32 v93, v218, v93, vcc
.LBB0_296:
	s_and_b64 vcc, exec, s[58:59]
	s_waitcnt lgkmcnt(1)
	v_mfma_f32_16x16x32_bf16 v[76:79], v[192:195], v[4:7], 0
	s_waitcnt lgkmcnt(0)
	v_mfma_f32_16x16x32_bf16 v[76:79], v[196:199], v[0:3], v[76:79]
	s_nop 7
	v_fma_f32 v96, v76, s18, -v103
	v_mov_b32_e32 v76, v77
	v_mov_b32_e32 v77, v78
	v_fma_f32 v78, v79, s18, -v107
	v_pk_fma_f32 v[76:77], v[76:77], s[18:19], v[104:105] op_sel_hi:[1,0,1] neg_lo:[0,0,1] neg_hi:[0,0,1]
	v_cndmask_b32_e64 v103, v218, v96, s[50:51]
	v_cndmask_b32_e64 v100, v218, v77, s[52:53]
	v_cndmask_b32_e64 v101, v218, v76, s[54:55]
	v_cndmask_b32_e64 v99, v218, v78, s[56:57]
	s_cbranch_vccnz .LBB0_298
	v_add_u32_e32 v76, s35, v233
	s_cmpk_gt_i32 s35, 0xff7f
	s_cselect_b64 s[14:15], -1, 0
	v_cmp_gt_i32_e32 vcc, s29, v76
	s_and_b64 vcc, s[14:15], vcc
	v_or_b32_e32 v77, 1, v76
	v_cndmask_b32_e32 v103, v218, v103, vcc
	v_cmp_gt_i32_e32 vcc, s29, v77
	s_and_b64 vcc, s[14:15], vcc
	v_or_b32_e32 v77, 2, v76
	v_cndmask_b32_e32 v101, v218, v101, vcc
	v_cmp_gt_i32_e32 vcc, s29, v77
	s_and_b64 vcc, s[14:15], vcc
	v_or_b32_e32 v76, 3, v76
	v_cndmask_b32_e32 v100, v218, v100, vcc
	v_cmp_gt_i32_e32 vcc, s29, v76
	s_and_b64 vcc, s[14:15], vcc
	s_nop 0
	v_cndmask_b32_e32 v99, v218, v99, vcc
